# gemm_in: the W-refill barrier now waits (lgkmcnt(3)) until every A-fragment read of the sub-step has returned, restoring the ordering guarantee the first-use read order had relaxed; otherwise identica
# baseline (speedup 1.0000x reference)
.Lgin_loop:
	s_waitcnt vmcnt(4)
	s_barrier
	ds_read_b128 v[230:233], v175 offset:0
	ds_read_b128 v[182:185], v176 offset:16384
	ds_read_b128 v[234:237], v175 offset:2048
	ds_read_b128 v[238:241], v175 offset:4096
	ds_read_b128 v[242:245], v175 offset:6144
	ds_read_b128 v[136:139], v177 offset:0
	ds_read_b128 v[140:143], v177 offset:2048
	ds_read_b128 v[144:147], v177 offset:4096
	ds_read_b128 v[148:151], v177 offset:6144
	ds_read_b128 v[186:189], v176 offset:18432
	ds_read_b128 v[190:193], v176 offset:20480
	ds_read_b128 v[194:197], v176 offset:22528
	s_add_u32 m0, s11, 0xc000
	s_waitcnt lgkmcnt(10)
	v_mfma_f32_16x16x32_f16 v[124:127], v[230:233], v[182:185], v[124:127]
	s_waitcnt lgkmcnt(9)
	v_mfma_f32_16x16x32_f16 v[92:95], v[234:237], v[182:185], v[92:95]
	s_waitcnt lgkmcnt(8)
	v_mfma_f32_16x16x32_f16 v[60:63], v[238:241], v[182:185], v[60:63]
	s_waitcnt lgkmcnt(7)
	v_mfma_f32_16x16x32_f16 v[28:31], v[242:245], v[182:185], v[28:31]
	global_load_lds_dwordx4 v128, s[6:7]
	s_waitcnt lgkmcnt(3)
	s_barrier
	ds_read_b128 v[198:201], v178 offset:16384
	ds_read_b128 v[202:205], v178 offset:18432
	ds_read_b128 v[222:225], v178 offset:20480
	ds_read_b128 v[226:229], v178 offset:22528
	s_add_u32 m0, s11, 0xd000
	s_waitcnt lgkmcnt(6)
	v_mfma_f32_16x16x32_f16 v[120:123], v[230:233], v[186:189], v[120:123]
	v_mfma_f32_16x16x32_f16 v[88:91], v[234:237], v[186:189], v[88:91]
	v_mfma_f32_16x16x32_f16 v[56:59], v[238:241], v[186:189], v[56:59]
	v_mfma_f32_16x16x32_f16 v[24:27], v[242:245], v[186:189], v[24:27]
	global_load_lds_dwordx4 v129, s[6:7]
	s_add_u32 m0, s11, 0xe000
	s_waitcnt lgkmcnt(5)
	v_mfma_f32_16x16x32_f16 v[116:119], v[230:233], v[190:193], v[116:119]
	v_mfma_f32_16x16x32_f16 v[84:87], v[234:237], v[190:193], v[84:87]
	v_mfma_f32_16x16x32_f16 v[52:55], v[238:241], v[190:193], v[52:55]
	v_mfma_f32_16x16x32_f16 v[20:23], v[242:245], v[190:193], v[20:23]
	global_load_lds_dwordx4 v132, s[6:7]
	s_add_u32 m0, s11, 0xf000
	s_waitcnt lgkmcnt(4)
	v_mfma_f32_16x16x32_f16 v[112:115], v[230:233], v[194:197], v[112:115]
	v_mfma_f32_16x16x32_f16 v[80:83], v[234:237], v[194:197], v[80:83]
	v_mfma_f32_16x16x32_f16 v[48:51], v[238:241], v[194:197], v[48:51]
	v_mfma_f32_16x16x32_f16 v[16:19], v[242:245], v[194:197], v[16:19]
	global_load_lds_dwordx4 v133, s[6:7]
	s_add_u32 m0, s11, 0x0
	s_waitcnt lgkmcnt(3)
	v_mfma_f32_16x16x32_f16 v[124:127], v[136:139], v[198:201], v[124:127]
	v_mfma_f32_16x16x32_f16 v[92:95], v[140:143], v[198:201], v[92:95]
	v_mfma_f32_16x16x32_f16 v[60:63], v[144:147], v[198:201], v[60:63]
	v_mfma_f32_16x16x32_f16 v[28:31], v[148:151], v[198:201], v[28:31]
	global_load_lds_dwordx4 v128, s[4:5]
	s_add_u32 m0, s11, 0x1000
	s_waitcnt lgkmcnt(2)
	v_mfma_f32_16x16x32_f16 v[120:123], v[136:139], v[202:205], v[120:123]
	v_mfma_f32_16x16x32_f16 v[88:91], v[140:143], v[202:205], v[88:91]
	v_mfma_f32_16x16x32_f16 v[56:59], v[144:147], v[202:205], v[56:59]
	v_mfma_f32_16x16x32_f16 v[24:27], v[148:151], v[202:205], v[24:27]
	global_load_lds_dwordx4 v129, s[4:5]
	s_add_u32 m0, s11, 0x2000
	s_waitcnt lgkmcnt(1)
	v_mfma_f32_16x16x32_f16 v[116:119], v[136:139], v[222:225], v[116:119]
	v_mfma_f32_16x16x32_f16 v[84:87], v[140:143], v[222:225], v[84:87]
	v_mfma_f32_16x16x32_f16 v[52:55], v[144:147], v[222:225], v[52:55]
	v_mfma_f32_16x16x32_f16 v[20:23], v[148:151], v[222:225], v[20:23]
	global_load_lds_dwordx4 v130, s[4:5]
	s_add_u32 m0, s11, 0x3000
	s_waitcnt lgkmcnt(0)
	v_mfma_f32_16x16x32_f16 v[112:115], v[136:139], v[226:229], v[112:115]
	v_mfma_f32_16x16x32_f16 v[80:83], v[140:143], v[226:229], v[80:83]
	v_mfma_f32_16x16x32_f16 v[48:51], v[144:147], v[226:229], v[48:51]
	v_mfma_f32_16x16x32_f16 v[16:19], v[148:151], v[226:229], v[16:19]
	global_load_lds_dwordx4 v131, s[4:5]
	s_add_u32 s6, s6, 128
	s_addc_u32 s7, s7, 0
	s_add_u32 s4, s4, 128
	s_addc_u32 s5, s5, 0
	s_waitcnt vmcnt(8)
	s_barrier
	ds_read_b128 v[182:185], v176 offset:32768
	ds_read_b128 v[186:189], v176 offset:34816
	ds_read_b128 v[190:193], v176 offset:36864
	ds_read_b128 v[194:197], v176 offset:38912
	ds_read_b128 v[198:201], v178 offset:32768
	ds_read_b128 v[202:205], v178 offset:34816
	ds_read_b128 v[222:225], v178 offset:36864
	ds_read_b128 v[226:229], v178 offset:38912
	s_add_u32 m0, s11, 0x4000
	s_waitcnt lgkmcnt(7)
	v_mfma_f32_16x16x32_f16 v[108:111], v[230:233], v[182:185], v[108:111]
	v_mfma_f32_16x16x32_f16 v[76:79], v[234:237], v[182:185], v[76:79]
	v_mfma_f32_16x16x32_f16 v[44:47], v[238:241], v[182:185], v[44:47]
	v_mfma_f32_16x16x32_f16 v[12:15], v[242:245], v[182:185], v[12:15]
	global_load_lds_dwordx4 v128, s[18:19]
	s_add_u32 m0, s11, 0x5000
	s_waitcnt lgkmcnt(6)
	v_mfma_f32_16x16x32_f16 v[104:107], v[230:233], v[186:189], v[104:107]
	v_mfma_f32_16x16x32_f16 v[72:75], v[234:237], v[186:189], v[72:75]
	v_mfma_f32_16x16x32_f16 v[40:43], v[238:241], v[186:189], v[40:43]
	v_mfma_f32_16x16x32_f16 v[8:11], v[242:245], v[186:189], v[8:11]
	global_load_lds_dwordx4 v129, s[18:19]
	s_add_u32 m0, s11, 0x6000
	s_waitcnt lgkmcnt(5)
	v_mfma_f32_16x16x32_f16 v[100:103], v[230:233], v[190:193], v[100:103]
	v_mfma_f32_16x16x32_f16 v[68:71], v[234:237], v[190:193], v[68:71]
	v_mfma_f32_16x16x32_f16 v[36:39], v[238:241], v[190:193], v[36:39]
	v_mfma_f32_16x16x32_f16 v[4:7], v[242:245], v[190:193], v[4:7]
	global_load_lds_dwordx4 v132, s[18:19]
	s_add_u32 m0, s11, 0x7000
	s_waitcnt lgkmcnt(4)
	v_mfma_f32_16x16x32_f16 v[96:99], v[230:233], v[194:197], v[96:99]
	v_mfma_f32_16x16x32_f16 v[64:67], v[234:237], v[194:197], v[64:67]
	v_mfma_f32_16x16x32_f16 v[32:35], v[238:241], v[194:197], v[32:35]
	v_mfma_f32_16x16x32_f16 v[0:3], v[242:245], v[194:197], v[0:3]
	global_load_lds_dwordx4 v133, s[18:19]
	s_waitcnt lgkmcnt(3)
	v_mfma_f32_16x16x32_f16 v[108:111], v[136:139], v[198:201], v[108:111]
	v_mfma_f32_16x16x32_f16 v[76:79], v[140:143], v[198:201], v[76:79]
	v_mfma_f32_16x16x32_f16 v[44:47], v[144:147], v[198:201], v[44:47]
	v_mfma_f32_16x16x32_f16 v[12:15], v[148:151], v[198:201], v[12:15]
	s_waitcnt lgkmcnt(2)
	v_mfma_f32_16x16x32_f16 v[104:107], v[136:139], v[202:205], v[104:107]
	v_mfma_f32_16x16x32_f16 v[72:75], v[140:143], v[202:205], v[72:75]
	v_mfma_f32_16x16x32_f16 v[40:43], v[144:147], v[202:205], v[40:43]
	v_mfma_f32_16x16x32_f16 v[8:11], v[148:151], v[202:205], v[8:11]
	s_waitcnt lgkmcnt(1)
	v_mfma_f32_16x16x32_f16 v[100:103], v[136:139], v[222:225], v[100:103]
	v_mfma_f32_16x16x32_f16 v[68:71], v[140:143], v[222:225], v[68:71]
	v_mfma_f32_16x16x32_f16 v[36:39], v[144:147], v[222:225], v[36:39]
	v_mfma_f32_16x16x32_f16 v[4:7], v[148:151], v[222:225], v[4:7]
	s_waitcnt lgkmcnt(0)
	v_mfma_f32_16x16x32_f16 v[96:99], v[136:139], v[226:229], v[96:99]
	v_mfma_f32_16x16x32_f16 v[64:67], v[140:143], v[226:229], v[64:67]
	v_mfma_f32_16x16x32_f16 v[32:35], v[144:147], v[226:229], v[32:35]
	v_mfma_f32_16x16x32_f16 v[0:3], v[148:151], v[226:229], v[0:3]
	s_add_u32 s18, s18, 128
	s_addc_u32 s19, s19, 0
	s_waitcnt vmcnt(4)
	s_barrier
	ds_read_b128 v[230:233], v175 offset:0
	ds_read_b128 v[182:185], v176 offset:49152
	ds_read_b128 v[234:237], v175 offset:2048
	ds_read_b128 v[238:241], v175 offset:4096
	ds_read_b128 v[242:245], v175 offset:6144
	ds_read_b128 v[136:139], v177 offset:0
	ds_read_b128 v[140:143], v177 offset:2048
	ds_read_b128 v[144:147], v177 offset:4096
	ds_read_b128 v[148:151], v177 offset:6144
	ds_read_b128 v[186:189], v176 offset:51200
	ds_read_b128 v[190:193], v176 offset:53248
	ds_read_b128 v[194:197], v176 offset:55296
	s_add_u32 m0, s11, 0x8000
	s_waitcnt lgkmcnt(10)
	v_mfma_f32_16x16x32_f16 v[124:127], v[230:233], v[182:185], v[124:127]
	s_waitcnt lgkmcnt(9)
	v_mfma_f32_16x16x32_f16 v[92:95], v[234:237], v[182:185], v[92:95]
	s_waitcnt lgkmcnt(8)
	v_mfma_f32_16x16x32_f16 v[60:63], v[238:241], v[182:185], v[60:63]
	s_waitcnt lgkmcnt(7)
	v_mfma_f32_16x16x32_f16 v[28:31], v[242:245], v[182:185], v[28:31]
	global_load_lds_dwordx4 v128, s[6:7]
	s_waitcnt lgkmcnt(3)
	s_barrier
	ds_read_b128 v[198:201], v178 offset:49152
	ds_read_b128 v[202:205], v178 offset:51200
	ds_read_b128 v[222:225], v178 offset:53248
	ds_read_b128 v[226:229], v178 offset:55296
	s_add_u32 m0, s11, 0x9000
	s_waitcnt lgkmcnt(6)
	v_mfma_f32_16x16x32_f16 v[120:123], v[230:233], v[186:189], v[120:123]
	v_mfma_f32_16x16x32_f16 v[88:91], v[234:237], v[186:189], v[88:91]
	v_mfma_f32_16x16x32_f16 v[56:59], v[238:241], v[186:189], v[56:59]
	v_mfma_f32_16x16x32_f16 v[24:27], v[242:245], v[186:189], v[24:27]
	global_load_lds_dwordx4 v129, s[6:7]
	s_add_u32 m0, s11, 0xa000
	s_waitcnt lgkmcnt(5)
	v_mfma_f32_16x16x32_f16 v[116:119], v[230:233], v[190:193], v[116:119]
	v_mfma_f32_16x16x32_f16 v[84:87], v[234:237], v[190:193], v[84:87]
	v_mfma_f32_16x16x32_f16 v[52:55], v[238:241], v[190:193], v[52:55]
	v_mfma_f32_16x16x32_f16 v[20:23], v[242:245], v[190:193], v[20:23]
	global_load_lds_dwordx4 v132, s[6:7]
	s_add_u32 m0, s11, 0xb000
	s_waitcnt lgkmcnt(4)
	v_mfma_f32_16x16x32_f16 v[112:115], v[230:233], v[194:197], v[112:115]
	v_mfma_f32_16x16x32_f16 v[80:83], v[234:237], v[194:197], v[80:83]
	v_mfma_f32_16x16x32_f16 v[48:51], v[238:241], v[194:197], v[48:51]
	v_mfma_f32_16x16x32_f16 v[16:19], v[242:245], v[194:197], v[16:19]
	global_load_lds_dwordx4 v133, s[6:7]
	s_add_u32 m0, s11, 0x0
	s_waitcnt lgkmcnt(3)
	v_mfma_f32_16x16x32_f16 v[124:127], v[136:139], v[198:201], v[124:127]
	v_mfma_f32_16x16x32_f16 v[92:95], v[140:143], v[198:201], v[92:95]
	v_mfma_f32_16x16x32_f16 v[60:63], v[144:147], v[198:201], v[60:63]
	v_mfma_f32_16x16x32_f16 v[28:31], v[148:151], v[198:201], v[28:31]
	global_load_lds_dwordx4 v128, s[4:5]
	s_add_u32 m0, s11, 0x1000
	s_waitcnt lgkmcnt(2)
	v_mfma_f32_16x16x32_f16 v[120:123], v[136:139], v[202:205], v[120:123]
	v_mfma_f32_16x16x32_f16 v[88:91], v[140:143], v[202:205], v[88:91]
	v_mfma_f32_16x16x32_f16 v[56:59], v[144:147], v[202:205], v[56:59]
	v_mfma_f32_16x16x32_f16 v[24:27], v[148:151], v[202:205], v[24:27]
	global_load_lds_dwordx4 v129, s[4:5]
	s_add_u32 m0, s11, 0x2000
	s_waitcnt lgkmcnt(1)
	v_mfma_f32_16x16x32_f16 v[116:119], v[136:139], v[222:225], v[116:119]
	v_mfma_f32_16x16x32_f16 v[84:87], v[140:143], v[222:225], v[84:87]
	v_mfma_f32_16x16x32_f16 v[52:55], v[144:147], v[222:225], v[52:55]
	v_mfma_f32_16x16x32_f16 v[20:23], v[148:151], v[222:225], v[20:23]
	global_load_lds_dwordx4 v130, s[4:5]
	s_add_u32 m0, s11, 0x3000
	s_waitcnt lgkmcnt(0)
	v_mfma_f32_16x16x32_f16 v[112:115], v[136:139], v[226:229], v[112:115]
	v_mfma_f32_16x16x32_f16 v[80:83], v[140:143], v[226:229], v[80:83]
	v_mfma_f32_16x16x32_f16 v[48:51], v[144:147], v[226:229], v[48:51]
	v_mfma_f32_16x16x32_f16 v[16:19], v[148:151], v[226:229], v[16:19]
	global_load_lds_dwordx4 v131, s[4:5]
	s_add_u32 s6, s6, 128
	s_addc_u32 s7, s7, 0
	s_add_u32 s4, s4, 128
	s_addc_u32 s5, s5, 0
	s_waitcnt vmcnt(8)
	s_barrier
	ds_read_b128 v[182:185], v176 offset:16384
	ds_read_b128 v[186:189], v176 offset:18432
	ds_read_b128 v[190:193], v176 offset:20480
	ds_read_b128 v[194:197], v176 offset:22528
	ds_read_b128 v[198:201], v178 offset:16384
	ds_read_b128 v[202:205], v178 offset:18432
	ds_read_b128 v[222:225], v178 offset:20480
	ds_read_b128 v[226:229], v178 offset:22528
	s_add_u32 m0, s11, 0xc000
	s_waitcnt lgkmcnt(7)
	v_mfma_f32_16x16x32_f16 v[108:111], v[230:233], v[182:185], v[108:111]
	v_mfma_f32_16x16x32_f16 v[76:79], v[234:237], v[182:185], v[76:79]
	v_mfma_f32_16x16x32_f16 v[44:47], v[238:241], v[182:185], v[44:47]
	v_mfma_f32_16x16x32_f16 v[12:15], v[242:245], v[182:185], v[12:15]
	global_load_lds_dwordx4 v128, s[18:19]
	s_add_u32 m0, s11, 0xd000
	s_waitcnt lgkmcnt(6)
	v_mfma_f32_16x16x32_f16 v[104:107], v[230:233], v[186:189], v[104:107]
	v_mfma_f32_16x16x32_f16 v[72:75], v[234:237], v[186:189], v[72:75]
	v_mfma_f32_16x16x32_f16 v[40:43], v[238:241], v[186:189], v[40:43]
	v_mfma_f32_16x16x32_f16 v[8:11], v[242:245], v[186:189], v[8:11]
	global_load_lds_dwordx4 v129, s[18:19]
	s_add_u32 m0, s11, 0xe000
	s_waitcnt lgkmcnt(5)
	v_mfma_f32_16x16x32_f16 v[100:103], v[230:233], v[190:193], v[100:103]
	v_mfma_f32_16x16x32_f16 v[68:71], v[234:237], v[190:193], v[68:71]
	v_mfma_f32_16x16x32_f16 v[36:39], v[238:241], v[190:193], v[36:39]
	v_mfma_f32_16x16x32_f16 v[4:7], v[242:245], v[190:193], v[4:7]
	global_load_lds_dwordx4 v132, s[18:19]
	s_add_u32 m0, s11, 0xf000
	s_waitcnt lgkmcnt(4)
	v_mfma_f32_16x16x32_f16 v[96:99], v[230:233], v[194:197], v[96:99]
	v_mfma_f32_16x16x32_f16 v[64:67], v[234:237], v[194:197], v[64:67]
	v_mfma_f32_16x16x32_f16 v[32:35], v[238:241], v[194:197], v[32:35]
	v_mfma_f32_16x16x32_f16 v[0:3], v[242:245], v[194:197], v[0:3]
	global_load_lds_dwordx4 v133, s[18:19]
	s_waitcnt lgkmcnt(3)
	v_mfma_f32_16x16x32_f16 v[108:111], v[136:139], v[198:201], v[108:111]
	v_mfma_f32_16x16x32_f16 v[76:79], v[140:143], v[198:201], v[76:79]
	v_mfma_f32_16x16x32_f16 v[44:47], v[144:147], v[198:201], v[44:47]
	v_mfma_f32_16x16x32_f16 v[12:15], v[148:151], v[198:201], v[12:15]
	s_waitcnt lgkmcnt(2)
	v_mfma_f32_16x16x32_f16 v[104:107], v[136:139], v[202:205], v[104:107]
	v_mfma_f32_16x16x32_f16 v[72:75], v[140:143], v[202:205], v[72:75]
	v_mfma_f32_16x16x32_f16 v[40:43], v[144:147], v[202:205], v[40:43]
	v_mfma_f32_16x16x32_f16 v[8:11], v[148:151], v[202:205], v[8:11]
	s_waitcnt lgkmcnt(1)
	v_mfma_f32_16x16x32_f16 v[100:103], v[136:139], v[222:225], v[100:103]
	v_mfma_f32_16x16x32_f16 v[68:71], v[140:143], v[222:225], v[68:71]
	v_mfma_f32_16x16x32_f16 v[36:39], v[144:147], v[222:225], v[36:39]
	v_mfma_f32_16x16x32_f16 v[4:7], v[148:151], v[222:225], v[4:7]
	s_waitcnt lgkmcnt(0)
	v_mfma_f32_16x16x32_f16 v[96:99], v[136:139], v[226:229], v[96:99]
	v_mfma_f32_16x16x32_f16 v[64:67], v[140:143], v[226:229], v[64:67]
	v_mfma_f32_16x16x32_f16 v[32:35], v[144:147], v[226:229], v[32:35]
	v_mfma_f32_16x16x32_f16 v[0:3], v[148:151], v[226:229], v[0:3]
	s_add_u32 s18, s18, 128
	s_addc_u32 s19, s19, 0
	s_waitcnt vmcnt(4)
	s_barrier
	ds_read_b128 v[230:233], v175 offset:0
	ds_read_b128 v[182:185], v176 offset:32768
	ds_read_b128 v[234:237], v175 offset:2048
	ds_read_b128 v[238:241], v175 offset:4096
	ds_read_b128 v[242:245], v175 offset:6144
	ds_read_b128 v[136:139], v177 offset:0
	ds_read_b128 v[140:143], v177 offset:2048
	ds_read_b128 v[144:147], v177 offset:4096
	ds_read_b128 v[148:151], v177 offset:6144
	ds_read_b128 v[186:189], v176 offset:34816
	ds_read_b128 v[190:193], v176 offset:36864
	ds_read_b128 v[194:197], v176 offset:38912
	s_add_u32 m0, s11, 0x4000
	s_waitcnt lgkmcnt(10)
	v_mfma_f32_16x16x32_f16 v[124:127], v[230:233], v[182:185], v[124:127]
	s_waitcnt lgkmcnt(9)
	v_mfma_f32_16x16x32_f16 v[92:95], v[234:237], v[182:185], v[92:95]
	s_waitcnt lgkmcnt(8)
	v_mfma_f32_16x16x32_f16 v[60:63], v[238:241], v[182:185], v[60:63]
	s_waitcnt lgkmcnt(7)
	v_mfma_f32_16x16x32_f16 v[28:31], v[242:245], v[182:185], v[28:31]
	global_load_lds_dwordx4 v128, s[6:7]
	s_waitcnt lgkmcnt(3)
	s_barrier
	ds_read_b128 v[198:201], v178 offset:32768
	ds_read_b128 v[202:205], v178 offset:34816
	ds_read_b128 v[222:225], v178 offset:36864
	ds_read_b128 v[226:229], v178 offset:38912
	s_add_u32 m0, s11, 0x5000
	s_waitcnt lgkmcnt(6)
	v_mfma_f32_16x16x32_f16 v[120:123], v[230:233], v[186:189], v[120:123]
	v_mfma_f32_16x16x32_f16 v[88:91], v[234:237], v[186:189], v[88:91]
	v_mfma_f32_16x16x32_f16 v[56:59], v[238:241], v[186:189], v[56:59]
	v_mfma_f32_16x16x32_f16 v[24:27], v[242:245], v[186:189], v[24:27]
	global_load_lds_dwordx4 v129, s[6:7]
	s_add_u32 m0, s11, 0x6000
	s_waitcnt lgkmcnt(5)
	v_mfma_f32_16x16x32_f16 v[116:119], v[230:233], v[190:193], v[116:119]
	v_mfma_f32_16x16x32_f16 v[84:87], v[234:237], v[190:193], v[84:87]
	v_mfma_f32_16x16x32_f16 v[52:55], v[238:241], v[190:193], v[52:55]
	v_mfma_f32_16x16x32_f16 v[20:23], v[242:245], v[190:193], v[20:23]
	global_load_lds_dwordx4 v132, s[6:7]
	s_add_u32 m0, s11, 0x7000
	s_waitcnt lgkmcnt(4)
	v_mfma_f32_16x16x32_f16 v[112:115], v[230:233], v[194:197], v[112:115]
	v_mfma_f32_16x16x32_f16 v[80:83], v[234:237], v[194:197], v[80:83]
	v_mfma_f32_16x16x32_f16 v[48:51], v[238:241], v[194:197], v[48:51]
	v_mfma_f32_16x16x32_f16 v[16:19], v[242:245], v[194:197], v[16:19]
	global_load_lds_dwordx4 v133, s[6:7]
	s_add_u32 m0, s11, 0x0
	s_waitcnt lgkmcnt(3)
	v_mfma_f32_16x16x32_f16 v[124:127], v[136:139], v[198:201], v[124:127]
	v_mfma_f32_16x16x32_f16 v[92:95], v[140:143], v[198:201], v[92:95]
	v_mfma_f32_16x16x32_f16 v[60:63], v[144:147], v[198:201], v[60:63]
	v_mfma_f32_16x16x32_f16 v[28:31], v[148:151], v[198:201], v[28:31]
	global_load_lds_dwordx4 v128, s[4:5]
	s_add_u32 m0, s11, 0x1000
	s_waitcnt lgkmcnt(2)
	v_mfma_f32_16x16x32_f16 v[120:123], v[136:139], v[202:205], v[120:123]
	v_mfma_f32_16x16x32_f16 v[88:91], v[140:143], v[202:205], v[88:91]
	v_mfma_f32_16x16x32_f16 v[56:59], v[144:147], v[202:205], v[56:59]
	v_mfma_f32_16x16x32_f16 v[24:27], v[148:151], v[202:205], v[24:27]
	global_load_lds_dwordx4 v129, s[4:5]
	s_add_u32 m0, s11, 0x2000
	s_waitcnt lgkmcnt(1)
	v_mfma_f32_16x16x32_f16 v[116:119], v[136:139], v[222:225], v[116:119]
	v_mfma_f32_16x16x32_f16 v[84:87], v[140:143], v[222:225], v[84:87]
	v_mfma_f32_16x16x32_f16 v[52:55], v[144:147], v[222:225], v[52:55]
	v_mfma_f32_16x16x32_f16 v[20:23], v[148:151], v[222:225], v[20:23]
	global_load_lds_dwordx4 v130, s[4:5]
	s_add_u32 m0, s11, 0x3000
	s_waitcnt lgkmcnt(0)
	v_mfma_f32_16x16x32_f16 v[112:115], v[136:139], v[226:229], v[112:115]
	v_mfma_f32_16x16x32_f16 v[80:83], v[140:143], v[226:229], v[80:83]
	v_mfma_f32_16x16x32_f16 v[48:51], v[144:147], v[226:229], v[48:51]
	v_mfma_f32_16x16x32_f16 v[16:19], v[148:151], v[226:229], v[16:19]
	global_load_lds_dwordx4 v131, s[4:5]
	s_add_u32 s6, s6, 128
	s_addc_u32 s7, s7, 0
	s_add_u32 s4, s4, 128
	s_addc_u32 s5, s5, 0
	s_waitcnt vmcnt(8)
	s_barrier
	ds_read_b128 v[182:185], v176 offset:49152
	ds_read_b128 v[186:189], v176 offset:51200
	ds_read_b128 v[190:193], v176 offset:53248
	ds_read_b128 v[194:197], v176 offset:55296
	ds_read_b128 v[198:201], v178 offset:49152
	ds_read_b128 v[202:205], v178 offset:51200
	ds_read_b128 v[222:225], v178 offset:53248
	ds_read_b128 v[226:229], v178 offset:55296
	s_add_u32 m0, s11, 0x8000
	s_waitcnt lgkmcnt(7)
	v_mfma_f32_16x16x32_f16 v[108:111], v[230:233], v[182:185], v[108:111]
	v_mfma_f32_16x16x32_f16 v[76:79], v[234:237], v[182:185], v[76:79]
	v_mfma_f32_16x16x32_f16 v[44:47], v[238:241], v[182:185], v[44:47]
	v_mfma_f32_16x16x32_f16 v[12:15], v[242:245], v[182:185], v[12:15]
	global_load_lds_dwordx4 v128, s[18:19]
	s_add_u32 m0, s11, 0x9000
	s_waitcnt lgkmcnt(6)
	v_mfma_f32_16x16x32_f16 v[104:107], v[230:233], v[186:189], v[104:107]
	v_mfma_f32_16x16x32_f16 v[72:75], v[234:237], v[186:189], v[72:75]
	v_mfma_f32_16x16x32_f16 v[40:43], v[238:241], v[186:189], v[40:43]
	v_mfma_f32_16x16x32_f16 v[8:11], v[242:245], v[186:189], v[8:11]
	global_load_lds_dwordx4 v129, s[18:19]
	s_add_u32 m0, s11, 0xa000
	s_waitcnt lgkmcnt(5)
	v_mfma_f32_16x16x32_f16 v[100:103], v[230:233], v[190:193], v[100:103]
	v_mfma_f32_16x16x32_f16 v[68:71], v[234:237], v[190:193], v[68:71]
	v_mfma_f32_16x16x32_f16 v[36:39], v[238:241], v[190:193], v[36:39]
	v_mfma_f32_16x16x32_f16 v[4:7], v[242:245], v[190:193], v[4:7]
	global_load_lds_dwordx4 v132, s[18:19]
	s_add_u32 m0, s11, 0xb000
	s_waitcnt lgkmcnt(4)
	v_mfma_f32_16x16x32_f16 v[96:99], v[230:233], v[194:197], v[96:99]
	v_mfma_f32_16x16x32_f16 v[64:67], v[234:237], v[194:197], v[64:67]
	v_mfma_f32_16x16x32_f16 v[32:35], v[238:241], v[194:197], v[32:35]
	v_mfma_f32_16x16x32_f16 v[0:3], v[242:245], v[194:197], v[0:3]
	global_load_lds_dwordx4 v133, s[18:19]
	s_waitcnt lgkmcnt(3)
	v_mfma_f32_16x16x32_f16 v[108:111], v[136:139], v[198:201], v[108:111]
	v_mfma_f32_16x16x32_f16 v[76:79], v[140:143], v[198:201], v[76:79]
	v_mfma_f32_16x16x32_f16 v[44:47], v[144:147], v[198:201], v[44:47]
	v_mfma_f32_16x16x32_f16 v[12:15], v[148:151], v[198:201], v[12:15]
	s_waitcnt lgkmcnt(2)
	v_mfma_f32_16x16x32_f16 v[104:107], v[136:139], v[202:205], v[104:107]
	v_mfma_f32_16x16x32_f16 v[72:75], v[140:143], v[202:205], v[72:75]
	v_mfma_f32_16x16x32_f16 v[40:43], v[144:147], v[202:205], v[40:43]
	v_mfma_f32_16x16x32_f16 v[8:11], v[148:151], v[202:205], v[8:11]
	s_waitcnt lgkmcnt(1)
	v_mfma_f32_16x16x32_f16 v[100:103], v[136:139], v[222:225], v[100:103]
	v_mfma_f32_16x16x32_f16 v[68:71], v[140:143], v[222:225], v[68:71]
	v_mfma_f32_16x16x32_f16 v[36:39], v[144:147], v[222:225], v[36:39]
	v_mfma_f32_16x16x32_f16 v[4:7], v[148:151], v[222:225], v[4:7]
	s_waitcnt lgkmcnt(0)
	v_mfma_f32_16x16x32_f16 v[96:99], v[136:139], v[226:229], v[96:99]
	v_mfma_f32_16x16x32_f16 v[64:67], v[140:143], v[226:229], v[64:67]
	v_mfma_f32_16x16x32_f16 v[32:35], v[144:147], v[226:229], v[32:35]
	v_mfma_f32_16x16x32_f16 v[0:3], v[148:151], v[226:229], v[0:3]
	s_add_u32 s18, s18, 128
	s_addc_u32 s19, s19, 0
	s_add_i32 s10, s10, 1
	s_cmp_lt_u32 s10, 10
	s_cbranch_scc1 .Lgin_loop
	s_waitcnt vmcnt(4)
	s_barrier
	ds_read_b128 v[230:233], v175 offset:0
	ds_read_b128 v[182:185], v176 offset:16384
	ds_read_b128 v[234:237], v175 offset:2048
	ds_read_b128 v[238:241], v175 offset:4096
	ds_read_b128 v[242:245], v175 offset:6144
	ds_read_b128 v[136:139], v177 offset:0
	ds_read_b128 v[140:143], v177 offset:2048
	ds_read_b128 v[144:147], v177 offset:4096
	ds_read_b128 v[148:151], v177 offset:6144
	ds_read_b128 v[186:189], v176 offset:18432
	ds_read_b128 v[190:193], v176 offset:20480
	ds_read_b128 v[194:197], v176 offset:22528
	s_add_u32 m0, s11, 0xc000
	s_waitcnt lgkmcnt(10)
	v_mfma_f32_16x16x32_f16 v[124:127], v[230:233], v[182:185], v[124:127]
	s_waitcnt lgkmcnt(9)
	v_mfma_f32_16x16x32_f16 v[92:95], v[234:237], v[182:185], v[92:95]
	s_waitcnt lgkmcnt(8)
	v_mfma_f32_16x16x32_f16 v[60:63], v[238:241], v[182:185], v[60:63]
	s_waitcnt lgkmcnt(7)
	v_mfma_f32_16x16x32_f16 v[28:31], v[242:245], v[182:185], v[28:31]
	global_load_lds_dwordx4 v128, s[6:7]
	s_waitcnt lgkmcnt(3)
	s_barrier
	ds_read_b128 v[198:201], v178 offset:16384
	ds_read_b128 v[202:205], v178 offset:18432
	ds_read_b128 v[222:225], v178 offset:20480
	ds_read_b128 v[226:229], v178 offset:22528
	s_add_u32 m0, s11, 0xd000
	s_waitcnt lgkmcnt(6)
	v_mfma_f32_16x16x32_f16 v[120:123], v[230:233], v[186:189], v[120:123]
	v_mfma_f32_16x16x32_f16 v[88:91], v[234:237], v[186:189], v[88:91]
	v_mfma_f32_16x16x32_f16 v[56:59], v[238:241], v[186:189], v[56:59]
	v_mfma_f32_16x16x32_f16 v[24:27], v[242:245], v[186:189], v[24:27]
	global_load_lds_dwordx4 v129, s[6:7]
	s_add_u32 m0, s11, 0xe000
	s_waitcnt lgkmcnt(5)
	v_mfma_f32_16x16x32_f16 v[116:119], v[230:233], v[190:193], v[116:119]
	v_mfma_f32_16x16x32_f16 v[84:87], v[234:237], v[190:193], v[84:87]
	v_mfma_f32_16x16x32_f16 v[52:55], v[238:241], v[190:193], v[52:55]
	v_mfma_f32_16x16x32_f16 v[20:23], v[242:245], v[190:193], v[20:23]
	global_load_lds_dwordx4 v132, s[6:7]
	s_add_u32 m0, s11, 0xf000
	s_waitcnt lgkmcnt(4)
	v_mfma_f32_16x16x32_f16 v[112:115], v[230:233], v[194:197], v[112:115]
	v_mfma_f32_16x16x32_f16 v[80:83], v[234:237], v[194:197], v[80:83]
	v_mfma_f32_16x16x32_f16 v[48:51], v[238:241], v[194:197], v[48:51]
	v_mfma_f32_16x16x32_f16 v[16:19], v[242:245], v[194:197], v[16:19]
	global_load_lds_dwordx4 v133, s[6:7]
	s_add_u32 m0, s11, 0x0
	s_waitcnt lgkmcnt(3)
	v_mfma_f32_16x16x32_f16 v[124:127], v[136:139], v[198:201], v[124:127]
	v_mfma_f32_16x16x32_f16 v[92:95], v[140:143], v[198:201], v[92:95]
	v_mfma_f32_16x16x32_f16 v[60:63], v[144:147], v[198:201], v[60:63]
	v_mfma_f32_16x16x32_f16 v[28:31], v[148:151], v[198:201], v[28:31]
	global_load_lds_dwordx4 v128, s[4:5]
	s_add_u32 m0, s11, 0x1000
	s_waitcnt lgkmcnt(2)
	v_mfma_f32_16x16x32_f16 v[120:123], v[136:139], v[202:205], v[120:123]
	v_mfma_f32_16x16x32_f16 v[88:91], v[140:143], v[202:205], v[88:91]
	v_mfma_f32_16x16x32_f16 v[56:59], v[144:147], v[202:205], v[56:59]
	v_mfma_f32_16x16x32_f16 v[24:27], v[148:151], v[202:205], v[24:27]
	global_load_lds_dwordx4 v129, s[4:5]
	s_add_u32 m0, s11, 0x2000
	s_waitcnt lgkmcnt(1)
	v_mfma_f32_16x16x32_f16 v[116:119], v[136:139], v[222:225], v[116:119]
	v_mfma_f32_16x16x32_f16 v[84:87], v[140:143], v[222:225], v[84:87]
	v_mfma_f32_16x16x32_f16 v[52:55], v[144:147], v[222:225], v[52:55]
	v_mfma_f32_16x16x32_f16 v[20:23], v[148:151], v[222:225], v[20:23]
	global_load_lds_dwordx4 v130, s[4:5]
	s_add_u32 m0, s11, 0x3000
	s_waitcnt lgkmcnt(0)
	v_mfma_f32_16x16x32_f16 v[112:115], v[136:139], v[226:229], v[112:115]
	v_mfma_f32_16x16x32_f16 v[80:83], v[140:143], v[226:229], v[80:83]
	v_mfma_f32_16x16x32_f16 v[48:51], v[144:147], v[226:229], v[48:51]
	v_mfma_f32_16x16x32_f16 v[16:19], v[148:151], v[226:229], v[16:19]
	global_load_lds_dwordx4 v131, s[4:5]
	s_add_u32 s6, s6, 128
	s_addc_u32 s7, s7, 0
	s_add_u32 s4, s4, 128
	s_addc_u32 s5, s5, 0
	s_waitcnt vmcnt(8)
	s_barrier
	ds_read_b128 v[182:185], v176 offset:32768
	ds_read_b128 v[186:189], v176 offset:34816
	ds_read_b128 v[190:193], v176 offset:36864
	ds_read_b128 v[194:197], v176 offset:38912
	ds_read_b128 v[198:201], v178 offset:32768
	ds_read_b128 v[202:205], v178 offset:34816
	ds_read_b128 v[222:225], v178 offset:36864
	ds_read_b128 v[226:229], v178 offset:38912
	s_add_u32 m0, s11, 0x4000
	s_waitcnt lgkmcnt(7)
	v_mfma_f32_16x16x32_f16 v[108:111], v[230:233], v[182:185], v[108:111]
	v_mfma_f32_16x16x32_f16 v[76:79], v[234:237], v[182:185], v[76:79]
	v_mfma_f32_16x16x32_f16 v[44:47], v[238:241], v[182:185], v[44:47]
	v_mfma_f32_16x16x32_f16 v[12:15], v[242:245], v[182:185], v[12:15]
	global_load_lds_dwordx4 v128, s[18:19]
	s_add_u32 m0, s11, 0x5000
	s_waitcnt lgkmcnt(6)
	v_mfma_f32_16x16x32_f16 v[104:107], v[230:233], v[186:189], v[104:107]
	v_mfma_f32_16x16x32_f16 v[72:75], v[234:237], v[186:189], v[72:75]
	v_mfma_f32_16x16x32_f16 v[40:43], v[238:241], v[186:189], v[40:43]
	v_mfma_f32_16x16x32_f16 v[8:11], v[242:245], v[186:189], v[8:11]
	global_load_lds_dwordx4 v129, s[18:19]
	s_add_u32 m0, s11, 0x6000
	s_waitcnt lgkmcnt(5)
	v_mfma_f32_16x16x32_f16 v[100:103], v[230:233], v[190:193], v[100:103]
	v_mfma_f32_16x16x32_f16 v[68:71], v[234:237], v[190:193], v[68:71]
	v_mfma_f32_16x16x32_f16 v[36:39], v[238:241], v[190:193], v[36:39]
	v_mfma_f32_16x16x32_f16 v[4:7], v[242:245], v[190:193], v[4:7]
	global_load_lds_dwordx4 v132, s[18:19]
	s_add_u32 m0, s11, 0x7000
	s_waitcnt lgkmcnt(4)
	v_mfma_f32_16x16x32_f16 v[96:99], v[230:233], v[194:197], v[96:99]
	v_mfma_f32_16x16x32_f16 v[64:67], v[234:237], v[194:197], v[64:67]
	v_mfma_f32_16x16x32_f16 v[32:35], v[238:241], v[194:197], v[32:35]
	v_mfma_f32_16x16x32_f16 v[0:3], v[242:245], v[194:197], v[0:3]
	global_load_lds_dwordx4 v133, s[18:19]
	s_waitcnt lgkmcnt(3)
	v_mfma_f32_16x16x32_f16 v[108:111], v[136:139], v[198:201], v[108:111]
	v_mfma_f32_16x16x32_f16 v[76:79], v[140:143], v[198:201], v[76:79]
	v_mfma_f32_16x16x32_f16 v[44:47], v[144:147], v[198:201], v[44:47]
	v_mfma_f32_16x16x32_f16 v[12:15], v[148:151], v[198:201], v[12:15]
	s_waitcnt lgkmcnt(2)
	v_mfma_f32_16x16x32_f16 v[104:107], v[136:139], v[202:205], v[104:107]
	v_mfma_f32_16x16x32_f16 v[72:75], v[140:143], v[202:205], v[72:75]
	v_mfma_f32_16x16x32_f16 v[40:43], v[144:147], v[202:205], v[40:43]
	v_mfma_f32_16x16x32_f16 v[8:11], v[148:151], v[202:205], v[8:11]
	s_waitcnt lgkmcnt(1)
	v_mfma_f32_16x16x32_f16 v[100:103], v[136:139], v[222:225], v[100:103]
	v_mfma_f32_16x16x32_f16 v[68:71], v[140:143], v[222:225], v[68:71]
	v_mfma_f32_16x16x32_f16 v[36:39], v[144:147], v[222:225], v[36:39]
	v_mfma_f32_16x16x32_f16 v[4:7], v[148:151], v[222:225], v[4:7]
	s_waitcnt lgkmcnt(0)
	v_mfma_f32_16x16x32_f16 v[96:99], v[136:139], v[226:229], v[96:99]
	v_mfma_f32_16x16x32_f16 v[64:67], v[140:143], v[226:229], v[64:67]
	v_mfma_f32_16x16x32_f16 v[32:35], v[144:147], v[226:229], v[32:35]
	v_mfma_f32_16x16x32_f16 v[0:3], v[148:151], v[226:229], v[0:3]
	s_add_u32 s18, s18, 128
	s_addc_u32 s19, s19, 0
	s_waitcnt vmcnt(4)
	s_barrier
	ds_read_b128 v[230:233], v175 offset:0
	ds_read_b128 v[182:185], v176 offset:49152
	ds_read_b128 v[234:237], v175 offset:2048
	ds_read_b128 v[238:241], v175 offset:4096
	ds_read_b128 v[242:245], v175 offset:6144
	ds_read_b128 v[136:139], v177 offset:0
	ds_read_b128 v[140:143], v177 offset:2048
	ds_read_b128 v[144:147], v177 offset:4096
	ds_read_b128 v[148:151], v177 offset:6144
	ds_read_b128 v[186:189], v176 offset:51200
	ds_read_b128 v[190:193], v176 offset:53248
	ds_read_b128 v[194:197], v176 offset:55296
	s_waitcnt lgkmcnt(10)
	v_mfma_f32_16x16x32_f16 v[124:127], v[230:233], v[182:185], v[124:127]
	s_waitcnt lgkmcnt(9)
	v_mfma_f32_16x16x32_f16 v[92:95], v[234:237], v[182:185], v[92:95]
	s_waitcnt lgkmcnt(8)
	v_mfma_f32_16x16x32_f16 v[60:63], v[238:241], v[182:185], v[60:63]
	s_waitcnt lgkmcnt(7)
	v_mfma_f32_16x16x32_f16 v[28:31], v[242:245], v[182:185], v[28:31]
	s_waitcnt lgkmcnt(3)
	s_barrier
	ds_read_b128 v[198:201], v178 offset:49152
	ds_read_b128 v[202:205], v178 offset:51200
	ds_read_b128 v[222:225], v178 offset:53248
	ds_read_b128 v[226:229], v178 offset:55296
	s_waitcnt lgkmcnt(6)
	v_mfma_f32_16x16x32_f16 v[120:123], v[230:233], v[186:189], v[120:123]
	v_mfma_f32_16x16x32_f16 v[88:91], v[234:237], v[186:189], v[88:91]
	v_mfma_f32_16x16x32_f16 v[56:59], v[238:241], v[186:189], v[56:59]
	v_mfma_f32_16x16x32_f16 v[24:27], v[242:245], v[186:189], v[24:27]
	s_waitcnt lgkmcnt(5)
	v_mfma_f32_16x16x32_f16 v[116:119], v[230:233], v[190:193], v[116:119]
	v_mfma_f32_16x16x32_f16 v[84:87], v[234:237], v[190:193], v[84:87]
	v_mfma_f32_16x16x32_f16 v[52:55], v[238:241], v[190:193], v[52:55]
	v_mfma_f32_16x16x32_f16 v[20:23], v[242:245], v[190:193], v[20:23]
	s_waitcnt lgkmcnt(4)
	v_mfma_f32_16x16x32_f16 v[112:115], v[230:233], v[194:197], v[112:115]
	v_mfma_f32_16x16x32_f16 v[80:83], v[234:237], v[194:197], v[80:83]
	v_mfma_f32_16x16x32_f16 v[48:51], v[238:241], v[194:197], v[48:51]
	v_mfma_f32_16x16x32_f16 v[16:19], v[242:245], v[194:197], v[16:19]
	s_waitcnt lgkmcnt(3)
	v_mfma_f32_16x16x32_f16 v[124:127], v[136:139], v[198:201], v[124:127]
	v_mfma_f32_16x16x32_f16 v[92:95], v[140:143], v[198:201], v[92:95]
	v_mfma_f32_16x16x32_f16 v[60:63], v[144:147], v[198:201], v[60:63]
	v_mfma_f32_16x16x32_f16 v[28:31], v[148:151], v[198:201], v[28:31]
	s_waitcnt lgkmcnt(2)
	v_mfma_f32_16x16x32_f16 v[120:123], v[136:139], v[202:205], v[120:123]
	v_mfma_f32_16x16x32_f16 v[88:91], v[140:143], v[202:205], v[88:91]
	v_mfma_f32_16x16x32_f16 v[56:59], v[144:147], v[202:205], v[56:59]
	v_mfma_f32_16x16x32_f16 v[24:27], v[148:151], v[202:205], v[24:27]
	s_waitcnt lgkmcnt(1)
	v_mfma_f32_16x16x32_f16 v[116:119], v[136:139], v[222:225], v[116:119]
	v_mfma_f32_16x16x32_f16 v[84:87], v[140:143], v[222:225], v[84:87]
	v_mfma_f32_16x16x32_f16 v[52:55], v[144:147], v[222:225], v[52:55]
	v_mfma_f32_16x16x32_f16 v[20:23], v[148:151], v[222:225], v[20:23]
	s_waitcnt lgkmcnt(0)
	v_mfma_f32_16x16x32_f16 v[112:115], v[136:139], v[226:229], v[112:115]
	v_mfma_f32_16x16x32_f16 v[80:83], v[140:143], v[226:229], v[80:83]
	v_mfma_f32_16x16x32_f16 v[48:51], v[144:147], v[226:229], v[48:51]
	v_mfma_f32_16x16x32_f16 v[16:19], v[148:151], v[226:229], v[16:19]
	s_waitcnt vmcnt(0)
	s_barrier
	ds_read_b128 v[182:185], v176 offset:16384
	ds_read_b128 v[186:189], v176 offset:18432
	ds_read_b128 v[190:193], v176 offset:20480
	ds_read_b128 v[194:197], v176 offset:22528
	ds_read_b128 v[198:201], v178 offset:16384
	ds_read_b128 v[202:205], v178 offset:18432
	ds_read_b128 v[222:225], v178 offset:20480
	ds_read_b128 v[226:229], v178 offset:22528
	s_waitcnt lgkmcnt(7)
	v_mfma_f32_16x16x32_f16 v[108:111], v[230:233], v[182:185], v[108:111]
	v_mfma_f32_16x16x32_f16 v[76:79], v[234:237], v[182:185], v[76:79]
	v_mfma_f32_16x16x32_f16 v[44:47], v[238:241], v[182:185], v[44:47]
	v_mfma_f32_16x16x32_f16 v[12:15], v[242:245], v[182:185], v[12:15]
	s_waitcnt lgkmcnt(6)
	v_mfma_f32_16x16x32_f16 v[104:107], v[230:233], v[186:189], v[104:107]
	v_mfma_f32_16x16x32_f16 v[72:75], v[234:237], v[186:189], v[72:75]
	v_mfma_f32_16x16x32_f16 v[40:43], v[238:241], v[186:189], v[40:43]
	v_mfma_f32_16x16x32_f16 v[8:11], v[242:245], v[186:189], v[8:11]
	s_waitcnt lgkmcnt(5)
	v_mfma_f32_16x16x32_f16 v[100:103], v[230:233], v[190:193], v[100:103]
	v_mfma_f32_16x16x32_f16 v[68:71], v[234:237], v[190:193], v[68:71]
	v_mfma_f32_16x16x32_f16 v[36:39], v[238:241], v[190:193], v[36:39]
	v_mfma_f32_16x16x32_f16 v[4:7], v[242:245], v[190:193], v[4:7]
	s_waitcnt lgkmcnt(4)
	v_mfma_f32_16x16x32_f16 v[96:99], v[230:233], v[194:197], v[96:99]
	v_mfma_f32_16x16x32_f16 v[64:67], v[234:237], v[194:197], v[64:67]
	v_mfma_f32_16x16x32_f16 v[32:35], v[238:241], v[194:197], v[32:35]
	v_mfma_f32_16x16x32_f16 v[0:3], v[242:245], v[194:197], v[0:3]
	s_waitcnt lgkmcnt(3)
	v_mfma_f32_16x16x32_f16 v[108:111], v[136:139], v[198:201], v[108:111]
	v_mfma_f32_16x16x32_f16 v[76:79], v[140:143], v[198:201], v[76:79]
	v_mfma_f32_16x16x32_f16 v[44:47], v[144:147], v[198:201], v[44:47]
	v_mfma_f32_16x16x32_f16 v[12:15], v[148:151], v[198:201], v[12:15]
	s_waitcnt lgkmcnt(2)
	v_mfma_f32_16x16x32_f16 v[104:107], v[136:139], v[202:205], v[104:107]
	v_mfma_f32_16x16x32_f16 v[72:75], v[140:143], v[202:205], v[72:75]
	v_mfma_f32_16x16x32_f16 v[40:43], v[144:147], v[202:205], v[40:43]
	v_mfma_f32_16x16x32_f16 v[8:11], v[148:151], v[202:205], v[8:11]
	s_waitcnt lgkmcnt(1)
	v_mfma_f32_16x16x32_f16 v[100:103], v[136:139], v[222:225], v[100:103]
	v_mfma_f32_16x16x32_f16 v[68:71], v[140:143], v[222:225], v[68:71]
	v_mfma_f32_16x16x32_f16 v[36:39], v[144:147], v[222:225], v[36:39]
	v_mfma_f32_16x16x32_f16 v[4:7], v[148:151], v[222:225], v[4:7]
	s_waitcnt lgkmcnt(0)
	v_mfma_f32_16x16x32_f16 v[96:99], v[136:139], v[226:229], v[96:99]
	v_mfma_f32_16x16x32_f16 v[64:67], v[140:143], v[226:229], v[64:67]
	v_mfma_f32_16x16x32_f16 v[32:35], v[144:147], v[226:229], v[32:35]
	v_mfma_f32_16x16x32_f16 v[0:3], v[148:151], v[226:229], v[0:3]
	s_nop 7
	s_cmpk_lt_u32 s9, 0x620
	s_cbranch_scc0 .Lgin_cls_lat
	s_cmp_lt_u32 s16, 4
	s_cbranch_scc1 .Lgin_plain
	s_sub_u32 s4, s16, 8
	s_cmp_lt_u32 s4, 28
	s_cbranch_scc1 .Lgin_plain
	s_sub_u32 s4, s16, 45
	s_cmp_lt_u32 s4, 3
	s_cbranch_scc1 .Lgin_plain
	s_sub_u32 s4, s16, 4
	s_cmp_lt_u32 s4, 2
	s_cbranch_scc1 .Lgin_kvar
	s_sub_u32 s4, s16, 37
	s_cmp_lt_u32 s4, 3
	s_cbranch_scc1 .Lgin_kvar
	s_sub_u32 s4, s16, 6
	s_cmp_lt_u32 s4, 2
	s_cbranch_scc1 .Lgin_vvar
	s_sub_u32 s4, s16, 41
	s_cmp_lt_u32 s4, 3
	s_cbranch_scc1 .Lgin_vvar
	s_branch .Lgin_notplain
